# scan loader flag poll with a single active lane and s_sleep 3 (less LDS traffic stolen from compute waves)
# speedup vs baseline: 1.0110x; 1.0110x over previous
.LBB0_498:
	s_andn2_saveexec_b64 s[52:53], s[52:53]
	s_cbranch_execz .LBB0_495
	s_cmpk_eq_i32 s58, 0x7f
	s_cbranch_scc1 .LBB0_495
	v_lshl_add_u64 v[14:15], v[8:9], 0, s[28:29]
	global_load_dwordx4 v[30:33], v[14:15], off
	v_lshl_add_u64 v[14:15], v[10:11], 0, s[28:29]
	v_add_co_u32_e32 v34, vcc, 0xd504000, v14
	v_lshl_add_u64 v[38:39], v[6:7], 0, s[28:29]
	s_nop 0
	v_addc_co_u32_e32 v35, vcc, 0, v15, vcc
	global_load_dwordx2 v[44:45], v[34:35], off
	v_add_co_u32_e32 v34, vcc, s60, v38
	s_xor_b32 s11, s54, 1
	s_nop 0
	v_addc_co_u32_e32 v35, vcc, 0, v39, vcc
	global_load_dwordx2 v[40:41], v[34:35], off
	v_add_co_u32_e32 v34, vcc, s61, v38
	s_mul_i32 s15, s11, 0xa000
	s_nop 0
	v_addc_co_u32_e32 v35, vcc, 0, v39, vcc
	global_load_dwordx2 v[46:47], v[34:35], off
	v_add_co_u32_e32 v34, vcc, 0xdd04000, v14
	s_add_i32 s15, s15, 0
	s_nop 0
	v_addc_co_u32_e32 v35, vcc, 0, v15, vcc
	global_load_dwordx2 v[48:49], v[34:35], off
	v_add_co_u32_e32 v34, vcc, 0xe504000, v14
	v_add_u32_e32 v29, s15, v21
	s_nop 0
	v_addc_co_u32_e32 v35, vcc, 0, v15, vcc
	v_add_co_u32_e32 v14, vcc, 0xed04000, v14
	global_load_dwordx2 v[50:51], v[34:35], off
	s_nop 0
	v_addc_co_u32_e32 v15, vcc, 0, v15, vcc
	v_add_co_u32_e32 v42, vcc, s62, v38
	global_load_dwordx2 v[14:15], v[14:15], off
	s_nop 0
	v_addc_co_u32_e32 v43, vcc, 0, v39, vcc
	v_add_co_u32_e32 v38, vcc, s63, v38
	v_lshl_add_u64 v[34:35], v[4:5], 0, s[28:29]
	global_load_dwordx2 v[52:53], v[42:43], off
	v_addc_co_u32_e32 v39, vcc, 0, v39, vcc
	global_load_dwordx4 v[34:37], v[34:35], off
	s_mulk_i32 s11, 0xa00
	global_load_dwordx2 v[54:55], v[38:39], off
	s_add_i32 s11, s11, 0
	v_add_u32_e32 v56, s15, v20
	s_add_i32 s11, s11, 0x14000
	v_mov_b32_e32 v57, 0x1f010
	s_movk_i32 s33, 0x4000
	s_mov_b64 s[98:99], exec
	s_mov_b64 exec, 1
.Lld_poll0:
	ds_read_b128 v[60:63], v57
	s_waitcnt lgkmcnt(0)
	v_min3_u32 v58, v60, v61, v62
	v_min_u32_e32 v58, v58, v63
	s_nop 0
	v_readfirstlane_b32 s41, v58
	s_cmp_ge_u32 s41, s58
	s_cbranch_scc1 .Lld_ok0
	s_sub_u32 s33, s33, 1
	s_cmp_eq_u32 s33, 0
	s_cbranch_scc1 .Lld_ok0
	s_sleep 3
	s_branch .Lld_poll0
.Lld_ok0:
	s_mov_b64 exec, s[98:99]
	s_waitcnt vmcnt(9)
	ds_write_b128 v29, v[30:33]
	s_waitcnt vmcnt(8)
	v_lshlrev_b32_e32 v42, 16, v44
	v_and_b32_e32 v43, 0xffff0000, v44
	v_lshlrev_b32_e32 v44, 16, v45
	v_and_b32_e32 v45, 0xffff0000, v45
	ds_write_b128 v29, v[42:45] offset:16
	s_waitcnt vmcnt(7)
	v_lshlrev_b32_e32 v30, 16, v40
	v_and_b32_e32 v31, 0xffff0000, v40
	v_lshlrev_b32_e32 v32, 16, v41
	v_and_b32_e32 v33, 0xffff0000, v41
	s_waitcnt vmcnt(6)
	v_lshlrev_b32_e32 v38, 16, v46
	v_and_b32_e32 v39, 0xffff0000, v46
	v_lshlrev_b32_e32 v40, 16, v47
	v_and_b32_e32 v41, 0xffff0000, v47
	s_waitcnt vmcnt(5)
	v_lshlrev_b32_e32 v42, 16, v48
	v_and_b32_e32 v43, 0xffff0000, v48
	v_lshlrev_b32_e32 v44, 16, v49
	v_and_b32_e32 v45, 0xffff0000, v49
	ds_write_b128 v29, v[42:45] offset:32
	s_waitcnt vmcnt(4)
	v_lshlrev_b32_e32 v42, 16, v50
	v_and_b32_e32 v43, 0xffff0000, v50
	v_lshlrev_b32_e32 v44, 16, v51
	v_and_b32_e32 v45, 0xffff0000, v51
	ds_write_b128 v29, v[42:45] offset:48
	s_waitcnt vmcnt(3)
	v_lshlrev_b32_e32 v42, 16, v14
	v_and_b32_e32 v43, 0xffff0000, v14
	v_lshlrev_b32_e32 v44, 16, v15
	v_and_b32_e32 v45, 0xffff0000, v15
	ds_write_b128 v29, v[42:45] offset:64
	s_waitcnt vmcnt(1)
	ds_write_b128 v56, v[34:37]
	ds_write_b128 v56, v[30:33] offset:16
	v_lshlrev_b32_e32 v30, 16, v52
	v_and_b32_e32 v31, 0xffff0000, v52
	v_lshlrev_b32_e32 v32, 16, v53
	v_and_b32_e32 v33, 0xffff0000, v53
	ds_write_b128 v56, v[30:33] offset:48
	s_waitcnt vmcnt(0)
	v_lshlrev_b32_e32 v30, 16, v54
	v_and_b32_e32 v31, 0xffff0000, v54
	v_lshlrev_b32_e32 v32, 16, v55
	v_and_b32_e32 v33, 0xffff0000, v55
	ds_write_b128 v56, v[38:41] offset:32
	ds_write_b128 v56, v[30:33] offset:64
	s_and_saveexec_b64 s[40:41], s[6:7]
	s_xor_b64 s[54:55], exec, s[40:41]
	s_cbranch_execz .LBB0_504
	s_and_saveexec_b64 s[56:57], s[8:9]
	s_cbranch_execz .LBB0_503
	v_lshl_add_u64 v[14:15], v[2:3], 0, s[28:29]
	global_load_dword v14, v[14:15], off
	v_add_u32_e32 v15, s11, v25
	s_waitcnt vmcnt(0)
	ds_write_b32 v15, v14 offset:64
